# scan operands fully double-buffered (prefetch 2 steps ahead, single lgkmcnt(6) wait per step)
# baseline (speedup 1.0000x reference)
; DEVI int ltid() { int t = __builtin_amdgcn_workitem_id_x(); asm volatile("" : "+v"(t)); return t; }
; __device__ void scan_block(const Params& P, int sb, unsigned char* lds) {
;     ...
;   const int head = sb >> 2, rg = sb & 3, tid = ltid();
;   const bool loader = tid >= 256; const int lt = tid - 256;
;   const int lane = tid & 63, wv = (tid >> 6) & 3, ks = lane & 15, myrow = wv * 4 + (lane >> 4);
;   f32x4 S = {0.f, 0.f, 0.f, 0.f};
;   const int hb = head * 64;
;     ...
;     for (int c = 0; c < NCH; ++c) {
;       const float* b = buf + (c & 1) * SC_STAGE;
;       const float* q = b + ks * 4;
;       const float* qv = b + 320 + myrow;
;       float* yo = Y + (size_t)(c * SC_CH + ks) * 1024 + hb + rg * 16 + myrow;
;       f32x4 w4 = *(const f32x4*)(q), k4 = *(const f32x4*)(q + 64), b4 = *(const f32x4*)(q + 128), kh4 = *(const f32x4*)(q + 192), r4 = *(const f32x4*)(q + 256);
;       float v = qv[0];
;       float yk = 0.f, ypart = 0.f;
; #pragma unroll
;       for (int s = 0; s < SC_CH; ++s) {
;         f32x4 w4n, k4n, b4n, kh4n, r4n; float vn;
;         if (s + 1 < SC_CH) {
;           const float* qn = q + (s + 1) * SC_STEP;
;           w4n = *(const f32x4*)(qn); k4n = *(const f32x4*)(qn + 64); b4n = *(const f32x4*)(qn + 128); kh4n = *(const f32x4*)(qn + 192); r4n = *(const f32x4*)(qn + 256);
;           vn = qv[(s + 1) * SC_STEP];
;         }
;         __builtin_amdgcn_sched_barrier(0);
;         if (s > 0) {
;           const float y = dpp_allreduce16(ypart);
;           yk = (ks == ((s - 1) & 15)) ? y : yk;
;           if (((s - 1) & 15) == 15) yo[(size_t)(s - 16) * 1024] = yk;
;         }
;         const f32x2 pp = (f32x2){S[0], S[1]} * (f32x2){k4[0], k4[1]} + (f32x2){S[2], S[3]} * (f32x2){k4[2], k4[3]};
;         const f32x4 A = S * w4 + v * kh4;
;         const float ar = dpp_allreduce16(pp.x + pp.y);
;         S = A + ar * b4;
;         const f32x2 yy = (f32x2){S[0], S[1]} * (f32x2){r4[0], r4[1]} + (f32x2){S[2], S[3]} * (f32x2){r4[2], r4[3]};
;         ypart = yy.x + yy.y;
;         if (s + 1 < SC_CH) { w4 = w4n; k4 = k4n; b4 = b4n; kh4 = kh4n; r4 = r4n; v = vn; }
;       }
;       { const float y = dpp_allreduce16(ypart); yk = (ks == 15) ? y : yk; yo[(size_t)16 * 1024] = yk; }
.LBB0_50:
	s_andn2_b64 vcc, exec, s[8:9]
	v_readlane_b32 s3, v252, 9
	s_cbranch_vccnz .LBB0_150
	v_readlane_b32 s2, v252, 0
	v_mov_b32_e32 v149, v169
	s_movk_i32 s0, 0x100
	s_nop 0
	v_cmp_gt_i32_e32 vcc, s0, v149
	s_lshl_b32 s0, s2, 4
	s_and_b32 s12, s0, 0xffffffc0
	s_barrier
	s_and_saveexec_b64 s[0:1], vcc
	s_xor_b64 s[82:83], exec, s[0:1]
	s_cbranch_execz .LBB0_55
	s_mov_b64 s[90:91], s[62:63]
	v_bfe_u32 v8, v149, 4, 4
	v_and_b32_e32 v0, 15, v149
	s_setprio 2
	s_ashr_i32 s13, s12, 31
	s_and_b32 s6, s2, 3
	s_lshl_b32 s8, s6, 6
	s_lshl_b64 s[6:7], s[12:13], 2
	s_add_u32 s6, s6, s8
	s_addc_u32 s7, s7, 0
	v_readlane_b32 s4, v251, 36
	v_readlane_b32 s5, v251, 37
	v_and_b32_e32 v2, 2, v0
	v_and_b32_e32 v3, 1, v0
	s_add_u32 s4, s4, s6
	s_addc_u32 s5, s5, s7
	v_cmp_ne_u32_e64 s[40:41], 0, v2
	v_cmp_ne_u32_e64 s[42:43], 0, v3
	v_lshl_add_u32 v9, v0, 4, 16
	v_lshl_add_u32 v10, v8, 2, 16
	v_bfrev_b32_e32 v2, v0
	v_lshrrev_b32_e32 v2, 16, v2
	v_lshl_add_u32 v2, v8, 2, v2
	v_add_u32_e32 v3, 0x10000, v2
	v_mov_b32_e32 v4, 0
	v_mov_b32_e32 v5, 0
	v_mov_b32_e32 v6, 0
	v_mov_b32_e32 v7, 0
	s_mov_b32 s3, 0
	s_waitcnt vmcnt(0)
	s_barrier
	ds_read_b128 v[12:15], v9 offset:256
	ds_read_b128 v[16:19], v9 offset:0
	ds_read_b128 v[20:23], v9 offset:768
	ds_read_b32 v24, v10 offset:1280
	ds_read_b128 v[44:47], v9 offset:512
	ds_read_b128 v[36:39], v9 offset:1024
	ds_read_b128 v[60:63], v9 offset:1600
	ds_read_b128 v[64:67], v9 offset:1344
	ds_read_b128 v[28:31], v9 offset:2112
	ds_read_b32 v32, v10 offset:2624
	ds_read_b128 v[48:51], v9 offset:1856
.Lscan_top:
	s_waitcnt lgkmcnt(6)
	v_pk_mul_f32 v[52:53], v[6:7], v[14:15]
	v_pk_mul_f32 v[56:57], v[6:7], v[18:19]
	v_pk_fma_f32 v[52:53], v[4:5], v[12:13], v[52:53]
	v_pk_mul_f32 v[54:55], v[4:5], v[16:17]
	v_add_f32_e32 v52, v52, v53
	ds_read_b128 v[12:15], v9 offset:2944
	ds_read_b128 v[16:19], v9 offset:2688
	v_add_f32_dpp v52, v52, v52 quad_perm:[1,0,3,2] row_mask:0xf bank_mask:0xf bound_ctrl:1
	v_pk_fma_f32 v[56:57], v[22:23], v[24:25], v[56:57] op_sel_hi:[1,0,1]
	v_pk_fma_f32 v[54:55], v[20:21], v[24:25], v[54:55] op_sel_hi:[1,0,1]
	v_add_f32_dpp v52, v52, v52 quad_perm:[2,3,0,1] row_mask:0xf bank_mask:0xf bound_ctrl:1
	ds_read_b128 v[20:23], v9 offset:3456
	ds_read_b32 v24, v10 offset:3968
	v_add_f32_dpp v52, v52, v52 row_half_mirror row_mask:0xf bank_mask:0xf bound_ctrl:1
	s_nop 1
	v_add_f32_dpp v52, v52, v52 row_mirror row_mask:0xf bank_mask:0xf bound_ctrl:1
	v_pk_fma_f32 v[6:7], v[46:47], v[52:53], v[56:57] op_sel_hi:[1,0,1]
	v_pk_fma_f32 v[4:5], v[44:45], v[52:53], v[54:55] op_sel_hi:[1,0,1]
	ds_read_b128 v[40:43], v9 offset:2368
	ds_read_b128 v[44:47], v9 offset:3200
	s_waitcnt lgkmcnt(6)
	v_pk_mul_f32 v[52:53], v[6:7], v[62:63]
	v_pk_mul_f32 v[56:57], v[6:7], v[66:67]
	v_pk_fma_f32 v[52:53], v[4:5], v[60:61], v[52:53]
	v_pk_mul_f32 v[54:55], v[4:5], v[64:65]
	v_add_f32_e32 v52, v52, v53
	ds_read_b128 v[60:63], v9 offset:4288
	ds_read_b128 v[64:67], v9 offset:4032
	v_add_f32_dpp v52, v52, v52 quad_perm:[1,0,3,2] row_mask:0xf bank_mask:0xf bound_ctrl:1
	v_pk_fma_f32 v[56:57], v[30:31], v[32:33], v[56:57] op_sel_hi:[1,0,1]
	v_pk_fma_f32 v[54:55], v[28:29], v[32:33], v[54:55] op_sel_hi:[1,0,1]
	v_add_f32_dpp v52, v52, v52 quad_perm:[2,3,0,1] row_mask:0xf bank_mask:0xf bound_ctrl:1
	ds_read_b128 v[28:31], v9 offset:4800
	ds_read_b32 v32, v10 offset:5312
	v_add_f32_dpp v52, v52, v52 row_half_mirror row_mask:0xf bank_mask:0xf bound_ctrl:1
	v_pk_mul_f32 v[26:27], v[6:7], v[38:39]
	s_nop 0
	v_add_f32_dpp v52, v52, v52 row_mirror row_mask:0xf bank_mask:0xf bound_ctrl:1
	v_pk_fma_f32 v[6:7], v[50:51], v[52:53], v[56:57] op_sel_hi:[1,0,1]
	v_pk_fma_f32 v[26:27], v[4:5], v[36:37], v[26:27]
	v_pk_fma_f32 v[4:5], v[48:49], v[52:53], v[54:55] op_sel_hi:[1,0,1]
	ds_read_b128 v[36:39], v9 offset:3712
	ds_read_b128 v[48:51], v9 offset:4544
	v_add_f32_e32 v25, v26, v27
	s_waitcnt lgkmcnt(6)
	v_pk_mul_f32 v[52:53], v[6:7], v[14:15]
	v_pk_mul_f32 v[56:57], v[6:7], v[18:19]
	v_pk_fma_f32 v[52:53], v[4:5], v[12:13], v[52:53]
	v_pk_mul_f32 v[54:55], v[4:5], v[16:17]
	v_add_f32_e32 v52, v52, v53
	ds_read_b128 v[12:15], v9 offset:5632
	ds_read_b128 v[16:19], v9 offset:5376
	v_add_f32_dpp v52, v52, v52 quad_perm:[1,0,3,2] row_mask:0xf bank_mask:0xf bound_ctrl:1
	v_pk_fma_f32 v[56:57], v[22:23], v[24:25], v[56:57] op_sel_hi:[1,0,1]
	v_pk_fma_f32 v[54:55], v[20:21], v[24:25], v[54:55] op_sel_hi:[1,0,1]
	v_add_f32_dpp v52, v52, v52 quad_perm:[2,3,0,1] row_mask:0xf bank_mask:0xf bound_ctrl:1
	ds_read_b128 v[20:23], v9 offset:6144
	ds_read_b32 v24, v10 offset:6656
	v_add_f32_dpp v52, v52, v52 row_half_mirror row_mask:0xf bank_mask:0xf bound_ctrl:1
	v_pk_mul_f32 v[26:27], v[6:7], v[42:43]
	v_add_f32_dpp v34, v25, v25 row_ror:8 row_mask:0xf bank_mask:0x3
	v_add_f32_dpp v52, v52, v52 row_mirror row_mask:0xf bank_mask:0xf bound_ctrl:1
	v_pk_fma_f32 v[6:7], v[46:47], v[52:53], v[56:57] op_sel_hi:[1,0,1]
	v_pk_fma_f32 v[26:27], v[4:5], v[40:41], v[26:27]
	v_pk_fma_f32 v[4:5], v[44:45], v[52:53], v[54:55] op_sel_hi:[1,0,1]
	ds_read_b128 v[40:43], v9 offset:5056
	ds_read_b128 v[44:47], v9 offset:5888
	v_add_f32_e32 v25, v26, v27
	s_waitcnt lgkmcnt(6)
; __device__ void scan_block(const Params& P, int sb, unsigned char* lds) {
;     ...
;       for (int s = 0; s < SC_CH; ++s) {
;         f32x4 w4n, k4n, b4n, kh4n, r4n; float vn;
;         if (s + 1 < SC_CH) {
;           const float* qn = q + (s + 1) * SC_STEP;
;           w4n = *(const f32x4*)(qn); k4n = *(const f32x4*)(qn + 64); b4n = *(const f32x4*)(qn + 128); kh4n = *(const f32x4*)(qn + 192); r4n = *(const f32x4*)(qn + 256);
;           vn = qv[(s + 1) * SC_STEP];
;         }
;         __builtin_amdgcn_sched_barrier(0);
;         if (s > 0) {
;           const float y = dpp_allreduce16(ypart);
;           yk = (ks == ((s - 1) & 15)) ? y : yk;
;           if (((s - 1) & 15) == 15) yo[(size_t)(s - 16) * 1024] = yk;
;         }
;         const f32x2 pp = (f32x2){S[0], S[1]} * (f32x2){k4[0], k4[1]} + (f32x2){S[2], S[3]} * (f32x2){k4[2], k4[3]};
;         const f32x4 A = S * w4 + v * kh4;
;         const float ar = dpp_allreduce16(pp.x + pp.y);
;         S = A + ar * b4;
;         const f32x2 yy = (f32x2){S[0], S[1]} * (f32x2){r4[0], r4[1]} + (f32x2){S[2], S[3]} * (f32x2){r4[2], r4[3]};
;         ypart = yy.x + yy.y;
;         if (s + 1 < SC_CH) { w4 = w4n; k4 = k4n; b4 = b4n; kh4 = kh4n; r4 = r4n; v = vn; }
;       }
	v_pk_mul_f32 v[52:53], v[6:7], v[62:63]
	v_pk_mul_f32 v[56:57], v[6:7], v[66:67]
	v_pk_fma_f32 v[52:53], v[4:5], v[60:61], v[52:53]
	v_pk_mul_f32 v[54:55], v[4:5], v[64:65]
	v_add_f32_e32 v52, v52, v53
	ds_read_b128 v[60:63], v9 offset:6976
	ds_read_b128 v[64:67], v9 offset:6720
	v_add_f32_dpp v52, v52, v52 quad_perm:[1,0,3,2] row_mask:0xf bank_mask:0xf bound_ctrl:1
	v_pk_fma_f32 v[56:57], v[30:31], v[32:33], v[56:57] op_sel_hi:[1,0,1]
	v_pk_fma_f32 v[54:55], v[28:29], v[32:33], v[54:55] op_sel_hi:[1,0,1]
	v_add_f32_dpp v52, v52, v52 quad_perm:[2,3,0,1] row_mask:0xf bank_mask:0xf bound_ctrl:1
	ds_read_b128 v[28:31], v9 offset:7488
	ds_read_b32 v32, v10 offset:8000
	v_add_f32_dpp v52, v52, v52 row_half_mirror row_mask:0xf bank_mask:0xf bound_ctrl:1
	v_pk_mul_f32 v[26:27], v[6:7], v[38:39]
	v_add_f32_dpp v34, v25, v25 row_ror:8 row_mask:0xf bank_mask:0xc
	v_add_f32_dpp v52, v52, v52 row_mirror row_mask:0xf bank_mask:0xf bound_ctrl:1
	v_pk_fma_f32 v[6:7], v[50:51], v[52:53], v[56:57] op_sel_hi:[1,0,1]
	v_pk_fma_f32 v[26:27], v[4:5], v[36:37], v[26:27]
	v_pk_fma_f32 v[4:5], v[48:49], v[52:53], v[54:55] op_sel_hi:[1,0,1]
	ds_read_b128 v[36:39], v9 offset:6400
	ds_read_b128 v[48:51], v9 offset:7232
	v_add_f32_e32 v25, v26, v27
	v_add_f32_dpp v35, v34, v34 row_half_mirror row_mask:0xf bank_mask:0x5
	s_waitcnt lgkmcnt(6)
	v_pk_mul_f32 v[52:53], v[6:7], v[14:15]
	v_pk_mul_f32 v[56:57], v[6:7], v[18:19]
	v_pk_fma_f32 v[52:53], v[4:5], v[12:13], v[52:53]
	v_pk_mul_f32 v[54:55], v[4:5], v[16:17]
	v_add_f32_e32 v52, v52, v53
	ds_read_b128 v[12:15], v9 offset:8320
	ds_read_b128 v[16:19], v9 offset:8064
	v_add_f32_dpp v52, v52, v52 quad_perm:[1,0,3,2] row_mask:0xf bank_mask:0xf bound_ctrl:1
	v_pk_fma_f32 v[56:57], v[22:23], v[24:25], v[56:57] op_sel_hi:[1,0,1]
	v_pk_fma_f32 v[54:55], v[20:21], v[24:25], v[54:55] op_sel_hi:[1,0,1]
	v_add_f32_dpp v52, v52, v52 quad_perm:[2,3,0,1] row_mask:0xf bank_mask:0xf bound_ctrl:1
	ds_read_b128 v[20:23], v9 offset:8832
	ds_read_b32 v24, v10 offset:9344
	v_add_f32_dpp v52, v52, v52 row_half_mirror row_mask:0xf bank_mask:0xf bound_ctrl:1
	v_pk_mul_f32 v[26:27], v[6:7], v[42:43]
	v_add_f32_dpp v34, v25, v25 row_ror:8 row_mask:0xf bank_mask:0x3
	v_add_f32_dpp v52, v52, v52 row_mirror row_mask:0xf bank_mask:0xf bound_ctrl:1
	v_pk_fma_f32 v[6:7], v[46:47], v[52:53], v[56:57] op_sel_hi:[1,0,1]
	v_pk_fma_f32 v[26:27], v[4:5], v[40:41], v[26:27]
	v_pk_fma_f32 v[4:5], v[44:45], v[52:53], v[54:55] op_sel_hi:[1,0,1]
	ds_read_b128 v[40:43], v9 offset:7744
	ds_read_b128 v[44:47], v9 offset:8576
	v_add_f32_e32 v25, v26, v27
	s_waitcnt lgkmcnt(6)
	v_pk_mul_f32 v[52:53], v[6:7], v[62:63]
	v_pk_mul_f32 v[56:57], v[6:7], v[66:67]
	v_pk_fma_f32 v[52:53], v[4:5], v[60:61], v[52:53]
	v_pk_mul_f32 v[54:55], v[4:5], v[64:65]
	v_add_f32_e32 v52, v52, v53
	ds_read_b128 v[60:63], v9 offset:9664
	ds_read_b128 v[64:67], v9 offset:9408
	v_add_f32_dpp v52, v52, v52 quad_perm:[1,0,3,2] row_mask:0xf bank_mask:0xf bound_ctrl:1
	v_pk_fma_f32 v[56:57], v[30:31], v[32:33], v[56:57] op_sel_hi:[1,0,1]
	v_pk_fma_f32 v[54:55], v[28:29], v[32:33], v[54:55] op_sel_hi:[1,0,1]
	v_add_f32_dpp v52, v52, v52 quad_perm:[2,3,0,1] row_mask:0xf bank_mask:0xf bound_ctrl:1
	ds_read_b128 v[28:31], v9 offset:10176
	ds_read_b32 v32, v10 offset:10688
	v_add_f32_dpp v52, v52, v52 row_half_mirror row_mask:0xf bank_mask:0xf bound_ctrl:1
	v_pk_mul_f32 v[26:27], v[6:7], v[38:39]
	v_add_f32_dpp v34, v25, v25 row_ror:8 row_mask:0xf bank_mask:0xc
	v_add_f32_dpp v52, v52, v52 row_mirror row_mask:0xf bank_mask:0xf bound_ctrl:1
	v_pk_fma_f32 v[6:7], v[50:51], v[52:53], v[56:57] op_sel_hi:[1,0,1]
	v_pk_fma_f32 v[26:27], v[4:5], v[36:37], v[26:27]
	v_pk_fma_f32 v[4:5], v[48:49], v[52:53], v[54:55] op_sel_hi:[1,0,1]
	ds_read_b128 v[36:39], v9 offset:9088
	ds_read_b128 v[48:51], v9 offset:9920
	v_add_f32_e32 v25, v26, v27
	v_add_f32_dpp v35, v34, v34 row_half_mirror row_mask:0xf bank_mask:0xa
	s_waitcnt lgkmcnt(6)
	v_pk_mul_f32 v[52:53], v[6:7], v[14:15]
	v_pk_mul_f32 v[56:57], v[6:7], v[18:19]
	v_pk_fma_f32 v[52:53], v[4:5], v[12:13], v[52:53]
	v_pk_mul_f32 v[54:55], v[4:5], v[16:17]
	v_add_f32_e32 v52, v52, v53
	ds_read_b128 v[12:15], v9 offset:11008
	ds_read_b128 v[16:19], v9 offset:10752
	v_add_f32_dpp v52, v52, v52 quad_perm:[1,0,3,2] row_mask:0xf bank_mask:0xf bound_ctrl:1
	v_pk_fma_f32 v[56:57], v[22:23], v[24:25], v[56:57] op_sel_hi:[1,0,1]
	v_pk_fma_f32 v[54:55], v[20:21], v[24:25], v[54:55] op_sel_hi:[1,0,1]
	v_add_f32_dpp v52, v52, v52 quad_perm:[2,3,0,1] row_mask:0xf bank_mask:0xf bound_ctrl:1
	ds_read_b128 v[20:23], v9 offset:11520
	ds_read_b32 v24, v10 offset:12032
	v_add_f32_dpp v52, v52, v52 row_half_mirror row_mask:0xf bank_mask:0xf bound_ctrl:1
	v_pk_mul_f32 v[26:27], v[6:7], v[42:43]
	v_add_f32_dpp v34, v25, v25 row_ror:8 row_mask:0xf bank_mask:0x3
	v_add_f32_dpp v52, v52, v52 row_mirror row_mask:0xf bank_mask:0xf bound_ctrl:1
	v_pk_fma_f32 v[6:7], v[46:47], v[52:53], v[56:57] op_sel_hi:[1,0,1]
	v_pk_fma_f32 v[26:27], v[4:5], v[40:41], v[26:27]
	v_pk_fma_f32 v[4:5], v[44:45], v[52:53], v[54:55] op_sel_hi:[1,0,1]
	ds_read_b128 v[40:43], v9 offset:10432
	ds_read_b128 v[44:47], v9 offset:11264
	v_add_f32_e32 v25, v26, v27
	s_waitcnt lgkmcnt(6)
; __device__ void scan_block(const Params& P, int sb, unsigned char* lds) {
;     ...
;       for (int s = 0; s < SC_CH; ++s) {
;         f32x4 w4n, k4n, b4n, kh4n, r4n; float vn;
;         if (s + 1 < SC_CH) {
;           const float* qn = q + (s + 1) * SC_STEP;
;           w4n = *(const f32x4*)(qn); k4n = *(const f32x4*)(qn + 64); b4n = *(const f32x4*)(qn + 128); kh4n = *(const f32x4*)(qn + 192); r4n = *(const f32x4*)(qn + 256);
;           vn = qv[(s + 1) * SC_STEP];
;         }
;         __builtin_amdgcn_sched_barrier(0);
;         if (s > 0) {
;           const float y = dpp_allreduce16(ypart);
;           yk = (ks == ((s - 1) & 15)) ? y : yk;
;           if (((s - 1) & 15) == 15) yo[(size_t)(s - 16) * 1024] = yk;
;         }
;         const f32x2 pp = (f32x2){S[0], S[1]} * (f32x2){k4[0], k4[1]} + (f32x2){S[2], S[3]} * (f32x2){k4[2], k4[3]};
;         const f32x4 A = S * w4 + v * kh4;
;         const float ar = dpp_allreduce16(pp.x + pp.y);
;         S = A + ar * b4;
;         const f32x2 yy = (f32x2){S[0], S[1]} * (f32x2){r4[0], r4[1]} + (f32x2){S[2], S[3]} * (f32x2){r4[2], r4[3]};
;         ypart = yy.x + yy.y;
;         if (s + 1 < SC_CH) { w4 = w4n; k4 = k4n; b4 = b4n; kh4 = kh4n; r4 = r4n; v = vn; }
;       }
	v_pk_mul_f32 v[52:53], v[6:7], v[62:63]
	v_pk_mul_f32 v[56:57], v[6:7], v[66:67]
	v_pk_fma_f32 v[52:53], v[4:5], v[60:61], v[52:53]
	v_pk_mul_f32 v[54:55], v[4:5], v[64:65]
	v_add_f32_e32 v52, v52, v53
	ds_read_b128 v[60:63], v9 offset:12352
	ds_read_b128 v[64:67], v9 offset:12096
	v_add_f32_dpp v52, v52, v52 quad_perm:[1,0,3,2] row_mask:0xf bank_mask:0xf bound_ctrl:1
	v_pk_fma_f32 v[56:57], v[30:31], v[32:33], v[56:57] op_sel_hi:[1,0,1]
	v_pk_fma_f32 v[54:55], v[28:29], v[32:33], v[54:55] op_sel_hi:[1,0,1]
	v_add_f32_dpp v52, v52, v52 quad_perm:[2,3,0,1] row_mask:0xf bank_mask:0xf bound_ctrl:1
	ds_read_b128 v[28:31], v9 offset:12864
	ds_read_b32 v32, v10 offset:13376
	v_add_f32_dpp v52, v52, v52 row_half_mirror row_mask:0xf bank_mask:0xf bound_ctrl:1
	v_pk_mul_f32 v[26:27], v[6:7], v[38:39]
	v_add_f32_dpp v34, v25, v25 row_ror:8 row_mask:0xf bank_mask:0xc
	v_add_f32_dpp v52, v52, v52 row_mirror row_mask:0xf bank_mask:0xf bound_ctrl:1
	v_pk_fma_f32 v[6:7], v[50:51], v[52:53], v[56:57] op_sel_hi:[1,0,1]
	v_pk_fma_f32 v[26:27], v[4:5], v[36:37], v[26:27]
	v_pk_fma_f32 v[4:5], v[48:49], v[52:53], v[54:55] op_sel_hi:[1,0,1]
	ds_read_b128 v[36:39], v9 offset:11776
	ds_read_b128 v[48:51], v9 offset:12608
	v_add_f32_e32 v25, v26, v27
	v_add_f32_dpp v58, v34, v34 row_half_mirror row_mask:0xf bank_mask:0x5
	s_waitcnt lgkmcnt(6)
	v_pk_mul_f32 v[52:53], v[6:7], v[14:15]
	v_pk_mul_f32 v[56:57], v[6:7], v[18:19]
	v_pk_fma_f32 v[52:53], v[4:5], v[12:13], v[52:53]
	v_pk_mul_f32 v[54:55], v[4:5], v[16:17]
	v_add_f32_e32 v52, v52, v53
	ds_read_b128 v[12:15], v9 offset:13696
	ds_read_b128 v[16:19], v9 offset:13440
	v_add_f32_dpp v52, v52, v52 quad_perm:[1,0,3,2] row_mask:0xf bank_mask:0xf bound_ctrl:1
	v_pk_fma_f32 v[56:57], v[22:23], v[24:25], v[56:57] op_sel_hi:[1,0,1]
	v_pk_fma_f32 v[54:55], v[20:21], v[24:25], v[54:55] op_sel_hi:[1,0,1]
	v_add_f32_dpp v52, v52, v52 quad_perm:[2,3,0,1] row_mask:0xf bank_mask:0xf bound_ctrl:1
	ds_read_b128 v[20:23], v9 offset:14208
	ds_read_b32 v24, v10 offset:14720
	v_add_f32_dpp v52, v52, v52 row_half_mirror row_mask:0xf bank_mask:0xf bound_ctrl:1
	v_pk_mul_f32 v[26:27], v[6:7], v[42:43]
	v_add_f32_dpp v34, v25, v25 row_ror:8 row_mask:0xf bank_mask:0x3
	v_add_f32_dpp v52, v52, v52 row_mirror row_mask:0xf bank_mask:0xf bound_ctrl:1
	v_pk_fma_f32 v[6:7], v[46:47], v[52:53], v[56:57] op_sel_hi:[1,0,1]
	v_pk_fma_f32 v[26:27], v[4:5], v[40:41], v[26:27]
	v_pk_fma_f32 v[4:5], v[44:45], v[52:53], v[54:55] op_sel_hi:[1,0,1]
	ds_read_b128 v[40:43], v9 offset:13120
	ds_read_b128 v[44:47], v9 offset:13952
	v_add_f32_e32 v25, v26, v27
	s_waitcnt lgkmcnt(6)
	v_pk_mul_f32 v[52:53], v[6:7], v[62:63]
	v_pk_mul_f32 v[56:57], v[6:7], v[66:67]
	v_pk_fma_f32 v[52:53], v[4:5], v[60:61], v[52:53]
	v_pk_mul_f32 v[54:55], v[4:5], v[64:65]
	v_add_f32_e32 v52, v52, v53
	ds_read_b128 v[60:63], v9 offset:15040
	ds_read_b128 v[64:67], v9 offset:14784
	v_add_f32_dpp v52, v52, v52 quad_perm:[1,0,3,2] row_mask:0xf bank_mask:0xf bound_ctrl:1
	v_pk_fma_f32 v[56:57], v[30:31], v[32:33], v[56:57] op_sel_hi:[1,0,1]
	v_pk_fma_f32 v[54:55], v[28:29], v[32:33], v[54:55] op_sel_hi:[1,0,1]
	v_add_f32_dpp v52, v52, v52 quad_perm:[2,3,0,1] row_mask:0xf bank_mask:0xf bound_ctrl:1
	ds_read_b128 v[28:31], v9 offset:15552
	ds_read_b32 v32, v10 offset:16064
	v_add_f32_dpp v52, v52, v52 row_half_mirror row_mask:0xf bank_mask:0xf bound_ctrl:1
	v_pk_mul_f32 v[26:27], v[6:7], v[38:39]
	v_add_f32_dpp v34, v25, v25 row_ror:8 row_mask:0xf bank_mask:0xc
	v_add_f32_dpp v52, v52, v52 row_mirror row_mask:0xf bank_mask:0xf bound_ctrl:1
	v_pk_fma_f32 v[6:7], v[50:51], v[52:53], v[56:57] op_sel_hi:[1,0,1]
	v_pk_fma_f32 v[26:27], v[4:5], v[36:37], v[26:27]
	v_pk_fma_f32 v[4:5], v[48:49], v[52:53], v[54:55] op_sel_hi:[1,0,1]
	ds_read_b128 v[36:39], v9 offset:14464
	ds_read_b128 v[48:51], v9 offset:15296
	v_add_f32_e32 v25, v26, v27
	v_add_f32_dpp v58, v34, v34 row_half_mirror row_mask:0xf bank_mask:0xa
	s_waitcnt lgkmcnt(6)
	v_pk_mul_f32 v[52:53], v[6:7], v[14:15]
	v_pk_mul_f32 v[56:57], v[6:7], v[18:19]
	v_pk_fma_f32 v[52:53], v[4:5], v[12:13], v[52:53]
	v_pk_mul_f32 v[54:55], v[4:5], v[16:17]
	v_add_f32_e32 v52, v52, v53
	ds_read_b128 v[12:15], v9 offset:16384
	ds_read_b128 v[16:19], v9 offset:16128
	v_add_f32_dpp v52, v52, v52 quad_perm:[1,0,3,2] row_mask:0xf bank_mask:0xf bound_ctrl:1
	v_pk_fma_f32 v[56:57], v[22:23], v[24:25], v[56:57] op_sel_hi:[1,0,1]
	v_pk_fma_f32 v[54:55], v[20:21], v[24:25], v[54:55] op_sel_hi:[1,0,1]
	v_add_f32_dpp v52, v52, v52 quad_perm:[2,3,0,1] row_mask:0xf bank_mask:0xf bound_ctrl:1
	ds_read_b128 v[20:23], v9 offset:16896
	ds_read_b32 v24, v10 offset:17408
	v_add_f32_dpp v52, v52, v52 row_half_mirror row_mask:0xf bank_mask:0xf bound_ctrl:1
	v_pk_mul_f32 v[26:27], v[6:7], v[42:43]
	v_add_f32_dpp v34, v25, v25 row_ror:8 row_mask:0xf bank_mask:0x3
	v_add_f32_dpp v52, v52, v52 row_mirror row_mask:0xf bank_mask:0xf bound_ctrl:1
	v_pk_fma_f32 v[6:7], v[46:47], v[52:53], v[56:57] op_sel_hi:[1,0,1]
	v_pk_fma_f32 v[26:27], v[4:5], v[40:41], v[26:27]
	v_pk_fma_f32 v[4:5], v[44:45], v[52:53], v[54:55] op_sel_hi:[1,0,1]
	ds_read_b128 v[40:43], v9 offset:15808
	ds_read_b128 v[44:47], v9 offset:16640
	v_add_f32_e32 v25, v26, v27
	v_cndmask_b32_e64 v255, v35, v58, s[40:41]
	s_waitcnt lgkmcnt(6)
; __device__ void scan_block(const Params& P, int sb, unsigned char* lds) {
;     ...
;       for (int s = 0; s < SC_CH; ++s) {
;         f32x4 w4n, k4n, b4n, kh4n, r4n; float vn;
;         if (s + 1 < SC_CH) {
;           const float* qn = q + (s + 1) * SC_STEP;
;           w4n = *(const f32x4*)(qn); k4n = *(const f32x4*)(qn + 64); b4n = *(const f32x4*)(qn + 128); kh4n = *(const f32x4*)(qn + 192); r4n = *(const f32x4*)(qn + 256);
;           vn = qv[(s + 1) * SC_STEP];
;         }
;         __builtin_amdgcn_sched_barrier(0);
;         if (s > 0) {
;           const float y = dpp_allreduce16(ypart);
;           yk = (ks == ((s - 1) & 15)) ? y : yk;
;           if (((s - 1) & 15) == 15) yo[(size_t)(s - 16) * 1024] = yk;
;         }
;         const f32x2 pp = (f32x2){S[0], S[1]} * (f32x2){k4[0], k4[1]} + (f32x2){S[2], S[3]} * (f32x2){k4[2], k4[3]};
;         const f32x4 A = S * w4 + v * kh4;
;         const float ar = dpp_allreduce16(pp.x + pp.y);
;         S = A + ar * b4;
;         const f32x2 yy = (f32x2){S[0], S[1]} * (f32x2){r4[0], r4[1]} + (f32x2){S[2], S[3]} * (f32x2){r4[2], r4[3]};
;         ypart = yy.x + yy.y;
;         if (s + 1 < SC_CH) { w4 = w4n; k4 = k4n; b4 = b4n; kh4 = kh4n; r4 = r4n; v = vn; }
;       }
	v_pk_mul_f32 v[52:53], v[6:7], v[62:63]
	v_pk_mul_f32 v[56:57], v[6:7], v[66:67]
	v_pk_fma_f32 v[52:53], v[4:5], v[60:61], v[52:53]
	v_pk_mul_f32 v[54:55], v[4:5], v[64:65]
	v_add_f32_e32 v52, v52, v53
	ds_read_b128 v[60:63], v9 offset:17728
	ds_read_b128 v[64:67], v9 offset:17472
	v_add_f32_dpp v52, v52, v52 quad_perm:[1,0,3,2] row_mask:0xf bank_mask:0xf bound_ctrl:1
	v_pk_fma_f32 v[56:57], v[30:31], v[32:33], v[56:57] op_sel_hi:[1,0,1]
	v_pk_fma_f32 v[54:55], v[28:29], v[32:33], v[54:55] op_sel_hi:[1,0,1]
	v_add_f32_dpp v52, v52, v52 quad_perm:[2,3,0,1] row_mask:0xf bank_mask:0xf bound_ctrl:1
	ds_read_b128 v[28:31], v9 offset:18240
	ds_read_b32 v32, v10 offset:18752
	v_add_f32_dpp v52, v52, v52 row_half_mirror row_mask:0xf bank_mask:0xf bound_ctrl:1
	v_pk_mul_f32 v[26:27], v[6:7], v[38:39]
	v_add_f32_dpp v34, v25, v25 row_ror:8 row_mask:0xf bank_mask:0xc
	v_add_f32_dpp v52, v52, v52 row_mirror row_mask:0xf bank_mask:0xf bound_ctrl:1
	v_pk_fma_f32 v[6:7], v[50:51], v[52:53], v[56:57] op_sel_hi:[1,0,1]
	v_pk_fma_f32 v[26:27], v[4:5], v[36:37], v[26:27]
	v_pk_fma_f32 v[4:5], v[48:49], v[52:53], v[54:55] op_sel_hi:[1,0,1]
	ds_read_b128 v[36:39], v9 offset:17152
	ds_read_b128 v[48:51], v9 offset:17984
	v_add_f32_e32 v25, v26, v27
	v_add_f32_dpp v0, v34, v34 row_half_mirror row_mask:0xf bank_mask:0x5
	s_waitcnt lgkmcnt(6)
	v_pk_mul_f32 v[52:53], v[6:7], v[14:15]
	v_pk_mul_f32 v[56:57], v[6:7], v[18:19]
	v_pk_fma_f32 v[52:53], v[4:5], v[12:13], v[52:53]
	v_pk_mul_f32 v[54:55], v[4:5], v[16:17]
	v_add_f32_e32 v52, v52, v53
	ds_read_b128 v[12:15], v9 offset:19072
	ds_read_b128 v[16:19], v9 offset:18816
	v_add_f32_dpp v52, v52, v52 quad_perm:[1,0,3,2] row_mask:0xf bank_mask:0xf bound_ctrl:1
	v_pk_fma_f32 v[56:57], v[22:23], v[24:25], v[56:57] op_sel_hi:[1,0,1]
	v_pk_fma_f32 v[54:55], v[20:21], v[24:25], v[54:55] op_sel_hi:[1,0,1]
	v_add_f32_dpp v52, v52, v52 quad_perm:[2,3,0,1] row_mask:0xf bank_mask:0xf bound_ctrl:1
	ds_read_b128 v[20:23], v9 offset:19584
	ds_read_b32 v24, v10 offset:20096
	v_add_f32_dpp v52, v52, v52 row_half_mirror row_mask:0xf bank_mask:0xf bound_ctrl:1
	v_pk_mul_f32 v[26:27], v[6:7], v[42:43]
	v_add_f32_dpp v34, v25, v25 row_ror:8 row_mask:0xf bank_mask:0x3
	v_add_f32_dpp v52, v52, v52 row_mirror row_mask:0xf bank_mask:0xf bound_ctrl:1
	v_pk_fma_f32 v[6:7], v[46:47], v[52:53], v[56:57] op_sel_hi:[1,0,1]
	v_pk_fma_f32 v[26:27], v[4:5], v[40:41], v[26:27]
	v_pk_fma_f32 v[4:5], v[44:45], v[52:53], v[54:55] op_sel_hi:[1,0,1]
	ds_read_b128 v[40:43], v9 offset:18496
	ds_read_b128 v[44:47], v9 offset:19328
	v_add_f32_e32 v25, v26, v27
	v_cndmask_b32_e64 v8, v58, v35, s[40:41]
	s_waitcnt lgkmcnt(6)
	v_pk_mul_f32 v[52:53], v[6:7], v[62:63]
	v_pk_mul_f32 v[56:57], v[6:7], v[66:67]
	v_pk_fma_f32 v[52:53], v[4:5], v[60:61], v[52:53]
	v_pk_mul_f32 v[54:55], v[4:5], v[64:65]
	v_add_f32_e32 v52, v52, v53
	ds_read_b128 v[60:63], v9 offset:20416
	ds_read_b128 v[64:67], v9 offset:20160
	v_add_f32_dpp v52, v52, v52 quad_perm:[1,0,3,2] row_mask:0xf bank_mask:0xf bound_ctrl:1
	v_pk_fma_f32 v[56:57], v[30:31], v[32:33], v[56:57] op_sel_hi:[1,0,1]
	v_pk_fma_f32 v[54:55], v[28:29], v[32:33], v[54:55] op_sel_hi:[1,0,1]
	v_add_f32_dpp v52, v52, v52 quad_perm:[2,3,0,1] row_mask:0xf bank_mask:0xf bound_ctrl:1
	ds_read_b128 v[28:31], v9 offset:20928
	ds_read_b32 v32, v10 offset:21440
	v_add_f32_dpp v52, v52, v52 row_half_mirror row_mask:0xf bank_mask:0xf bound_ctrl:1
	v_pk_mul_f32 v[26:27], v[6:7], v[38:39]
	v_add_f32_dpp v34, v25, v25 row_ror:8 row_mask:0xf bank_mask:0xc
	v_add_f32_dpp v52, v52, v52 row_mirror row_mask:0xf bank_mask:0xf bound_ctrl:1
	v_pk_fma_f32 v[6:7], v[50:51], v[52:53], v[56:57] op_sel_hi:[1,0,1]
	v_pk_fma_f32 v[26:27], v[4:5], v[36:37], v[26:27]
	v_pk_fma_f32 v[4:5], v[48:49], v[52:53], v[54:55] op_sel_hi:[1,0,1]
	ds_read_b128 v[36:39], v9 offset:19840
	ds_read_b128 v[48:51], v9 offset:20672
	v_add_f32_e32 v25, v26, v27
	v_add_f32_dpp v0, v34, v34 row_half_mirror row_mask:0xf bank_mask:0xa
	s_waitcnt lgkmcnt(6)
	v_pk_mul_f32 v[52:53], v[6:7], v[14:15]
	v_pk_mul_f32 v[56:57], v[6:7], v[18:19]
	v_pk_fma_f32 v[52:53], v[4:5], v[12:13], v[52:53]
	v_pk_mul_f32 v[54:55], v[4:5], v[16:17]
	v_add_f32_e32 v52, v52, v53
	ds_read_b128 v[12:15], v9 offset:21760
	ds_read_b128 v[16:19], v9 offset:21504
	v_add_f32_dpp v52, v52, v52 quad_perm:[1,0,3,2] row_mask:0xf bank_mask:0xf bound_ctrl:1
	v_pk_fma_f32 v[56:57], v[22:23], v[24:25], v[56:57] op_sel_hi:[1,0,1]
	v_pk_fma_f32 v[54:55], v[20:21], v[24:25], v[54:55] op_sel_hi:[1,0,1]
	v_add_f32_dpp v52, v52, v52 quad_perm:[2,3,0,1] row_mask:0xf bank_mask:0xf bound_ctrl:1
	ds_read_b128 v[20:23], v9 offset:22272
	ds_read_b32 v24, v10 offset:22784
	v_add_f32_dpp v52, v52, v52 row_half_mirror row_mask:0xf bank_mask:0xf bound_ctrl:1
	v_pk_mul_f32 v[26:27], v[6:7], v[42:43]
	v_add_f32_dpp v34, v25, v25 row_ror:8 row_mask:0xf bank_mask:0x3
	v_add_f32_dpp v52, v52, v52 row_mirror row_mask:0xf bank_mask:0xf bound_ctrl:1
	v_pk_fma_f32 v[6:7], v[46:47], v[52:53], v[56:57] op_sel_hi:[1,0,1]
	v_pk_fma_f32 v[26:27], v[4:5], v[40:41], v[26:27]
	v_pk_fma_f32 v[4:5], v[44:45], v[52:53], v[54:55] op_sel_hi:[1,0,1]
	ds_read_b128 v[40:43], v9 offset:21184
	ds_read_b128 v[44:47], v9 offset:22016
	v_add_f32_e32 v25, v26, v27
	v_add_f32_dpp v253, v8, v255 quad_perm:[2,3,0,1] row_mask:0xf bank_mask:0xf bound_ctrl:1
	s_waitcnt lgkmcnt(6)
; __device__ void scan_block(const Params& P, int sb, unsigned char* lds) {
;     ...
;       for (int s = 0; s < SC_CH; ++s) {
;         f32x4 w4n, k4n, b4n, kh4n, r4n; float vn;
;         if (s + 1 < SC_CH) {
;           const float* qn = q + (s + 1) * SC_STEP;
;           w4n = *(const f32x4*)(qn); k4n = *(const f32x4*)(qn + 64); b4n = *(const f32x4*)(qn + 128); kh4n = *(const f32x4*)(qn + 192); r4n = *(const f32x4*)(qn + 256);
;           vn = qv[(s + 1) * SC_STEP];
;         }
;         __builtin_amdgcn_sched_barrier(0);
;         if (s > 0) {
;           const float y = dpp_allreduce16(ypart);
;           yk = (ks == ((s - 1) & 15)) ? y : yk;
;           if (((s - 1) & 15) == 15) yo[(size_t)(s - 16) * 1024] = yk;
;         }
;         const f32x2 pp = (f32x2){S[0], S[1]} * (f32x2){k4[0], k4[1]} + (f32x2){S[2], S[3]} * (f32x2){k4[2], k4[3]};
;         const f32x4 A = S * w4 + v * kh4;
;         const float ar = dpp_allreduce16(pp.x + pp.y);
;         S = A + ar * b4;
;         const f32x2 yy = (f32x2){S[0], S[1]} * (f32x2){r4[0], r4[1]} + (f32x2){S[2], S[3]} * (f32x2){r4[2], r4[3]};
;         ypart = yy.x + yy.y;
;         if (s + 1 < SC_CH) { w4 = w4n; k4 = k4n; b4 = b4n; kh4 = kh4n; r4 = r4n; v = vn; }
;       }
	v_pk_mul_f32 v[52:53], v[6:7], v[62:63]
	v_pk_mul_f32 v[56:57], v[6:7], v[66:67]
	v_pk_fma_f32 v[52:53], v[4:5], v[60:61], v[52:53]
	v_pk_mul_f32 v[54:55], v[4:5], v[64:65]
	v_add_f32_e32 v52, v52, v53
	ds_read_b128 v[60:63], v9 offset:23104
	ds_read_b128 v[64:67], v9 offset:22848
	v_add_f32_dpp v52, v52, v52 quad_perm:[1,0,3,2] row_mask:0xf bank_mask:0xf bound_ctrl:1
	v_pk_fma_f32 v[56:57], v[30:31], v[32:33], v[56:57] op_sel_hi:[1,0,1]
	v_pk_fma_f32 v[54:55], v[28:29], v[32:33], v[54:55] op_sel_hi:[1,0,1]
	v_add_f32_dpp v52, v52, v52 quad_perm:[2,3,0,1] row_mask:0xf bank_mask:0xf bound_ctrl:1
	ds_read_b128 v[28:31], v9 offset:23616
	ds_read_b32 v32, v10 offset:24128
	v_add_f32_dpp v52, v52, v52 row_half_mirror row_mask:0xf bank_mask:0xf bound_ctrl:1
	v_pk_mul_f32 v[26:27], v[6:7], v[38:39]
	v_add_f32_dpp v34, v25, v25 row_ror:8 row_mask:0xf bank_mask:0xc
	v_add_f32_dpp v52, v52, v52 row_mirror row_mask:0xf bank_mask:0xf bound_ctrl:1
	v_pk_fma_f32 v[6:7], v[50:51], v[52:53], v[56:57] op_sel_hi:[1,0,1]
	v_pk_fma_f32 v[26:27], v[4:5], v[36:37], v[26:27]
	v_pk_fma_f32 v[4:5], v[48:49], v[52:53], v[54:55] op_sel_hi:[1,0,1]
	ds_read_b128 v[36:39], v9 offset:22528
	ds_read_b128 v[48:51], v9 offset:23360
	v_add_f32_e32 v25, v26, v27
	v_add_f32_dpp v11, v34, v34 row_half_mirror row_mask:0xf bank_mask:0x5
	s_waitcnt lgkmcnt(6)
	v_pk_mul_f32 v[52:53], v[6:7], v[14:15]
	v_pk_mul_f32 v[56:57], v[6:7], v[18:19]
	v_pk_fma_f32 v[52:53], v[4:5], v[12:13], v[52:53]
	v_pk_mul_f32 v[54:55], v[4:5], v[16:17]
	v_add_f32_e32 v52, v52, v53
	ds_read_b128 v[12:15], v9 offset:24448
	ds_read_b128 v[16:19], v9 offset:24192
	v_add_f32_dpp v52, v52, v52 quad_perm:[1,0,3,2] row_mask:0xf bank_mask:0xf bound_ctrl:1
	v_pk_fma_f32 v[56:57], v[22:23], v[24:25], v[56:57] op_sel_hi:[1,0,1]
	v_pk_fma_f32 v[54:55], v[20:21], v[24:25], v[54:55] op_sel_hi:[1,0,1]
	v_add_f32_dpp v52, v52, v52 quad_perm:[2,3,0,1] row_mask:0xf bank_mask:0xf bound_ctrl:1
	ds_read_b128 v[20:23], v9 offset:24960
	ds_read_b32 v24, v10 offset:25472
	v_add_f32_dpp v52, v52, v52 row_half_mirror row_mask:0xf bank_mask:0xf bound_ctrl:1
	v_pk_mul_f32 v[26:27], v[6:7], v[42:43]
	v_add_f32_dpp v34, v25, v25 row_ror:8 row_mask:0xf bank_mask:0x3
	v_add_f32_dpp v52, v52, v52 row_mirror row_mask:0xf bank_mask:0xf bound_ctrl:1
	v_pk_fma_f32 v[6:7], v[46:47], v[52:53], v[56:57] op_sel_hi:[1,0,1]
	v_pk_fma_f32 v[26:27], v[4:5], v[40:41], v[26:27]
	v_pk_fma_f32 v[4:5], v[44:45], v[52:53], v[54:55] op_sel_hi:[1,0,1]
	ds_read_b128 v[40:43], v9 offset:23872
	ds_read_b128 v[44:47], v9 offset:24704
	v_add_f32_e32 v25, v26, v27
	s_waitcnt lgkmcnt(6)
	v_pk_mul_f32 v[52:53], v[6:7], v[62:63]
	v_pk_mul_f32 v[56:57], v[6:7], v[66:67]
	v_pk_fma_f32 v[52:53], v[4:5], v[60:61], v[52:53]
	v_pk_mul_f32 v[54:55], v[4:5], v[64:65]
	v_add_f32_e32 v52, v52, v53
	ds_read_b128 v[60:63], v9 offset:25792
	ds_read_b128 v[64:67], v9 offset:25536
	v_add_f32_dpp v52, v52, v52 quad_perm:[1,0,3,2] row_mask:0xf bank_mask:0xf bound_ctrl:1
	v_pk_fma_f32 v[56:57], v[30:31], v[32:33], v[56:57] op_sel_hi:[1,0,1]
	v_pk_fma_f32 v[54:55], v[28:29], v[32:33], v[54:55] op_sel_hi:[1,0,1]
	v_add_f32_dpp v52, v52, v52 quad_perm:[2,3,0,1] row_mask:0xf bank_mask:0xf bound_ctrl:1
	ds_read_b128 v[28:31], v9 offset:26304
	ds_read_b32 v32, v10 offset:26816
	v_add_f32_dpp v52, v52, v52 row_half_mirror row_mask:0xf bank_mask:0xf bound_ctrl:1
	v_pk_mul_f32 v[26:27], v[6:7], v[38:39]
	v_add_f32_dpp v34, v25, v25 row_ror:8 row_mask:0xf bank_mask:0xc
	v_add_f32_dpp v52, v52, v52 row_mirror row_mask:0xf bank_mask:0xf bound_ctrl:1
	v_pk_fma_f32 v[6:7], v[50:51], v[52:53], v[56:57] op_sel_hi:[1,0,1]
	v_pk_fma_f32 v[26:27], v[4:5], v[36:37], v[26:27]
	v_pk_fma_f32 v[4:5], v[48:49], v[52:53], v[54:55] op_sel_hi:[1,0,1]
	ds_read_b128 v[36:39], v9 offset:25216
	ds_read_b128 v[48:51], v9 offset:26048
	v_add_f32_e32 v25, v26, v27
	v_add_f32_dpp v11, v34, v34 row_half_mirror row_mask:0xf bank_mask:0xa
	s_waitcnt lgkmcnt(6)
	v_pk_mul_f32 v[52:53], v[6:7], v[14:15]
	v_pk_mul_f32 v[56:57], v[6:7], v[18:19]
	v_pk_fma_f32 v[52:53], v[4:5], v[12:13], v[52:53]
	v_pk_mul_f32 v[54:55], v[4:5], v[16:17]
	v_add_f32_e32 v52, v52, v53
	ds_read_b128 v[12:15], v9 offset:27136
	ds_read_b128 v[16:19], v9 offset:26880
	v_add_f32_dpp v52, v52, v52 quad_perm:[1,0,3,2] row_mask:0xf bank_mask:0xf bound_ctrl:1
	v_pk_fma_f32 v[56:57], v[22:23], v[24:25], v[56:57] op_sel_hi:[1,0,1]
	v_pk_fma_f32 v[54:55], v[20:21], v[24:25], v[54:55] op_sel_hi:[1,0,1]
	v_add_f32_dpp v52, v52, v52 quad_perm:[2,3,0,1] row_mask:0xf bank_mask:0xf bound_ctrl:1
	ds_read_b128 v[20:23], v9 offset:27648
	ds_read_b32 v24, v10 offset:28160
	v_add_f32_dpp v52, v52, v52 row_half_mirror row_mask:0xf bank_mask:0xf bound_ctrl:1
	v_pk_mul_f32 v[26:27], v[6:7], v[42:43]
	v_add_f32_dpp v34, v25, v25 row_ror:8 row_mask:0xf bank_mask:0x3
	v_add_f32_dpp v52, v52, v52 row_mirror row_mask:0xf bank_mask:0xf bound_ctrl:1
	v_pk_fma_f32 v[6:7], v[46:47], v[52:53], v[56:57] op_sel_hi:[1,0,1]
	v_pk_fma_f32 v[26:27], v[4:5], v[40:41], v[26:27]
	v_pk_fma_f32 v[4:5], v[44:45], v[52:53], v[54:55] op_sel_hi:[1,0,1]
	ds_read_b128 v[40:43], v9 offset:26560
	ds_read_b128 v[44:47], v9 offset:27392
	v_add_f32_e32 v25, v26, v27
	v_cndmask_b32_e64 v255, v0, v11, s[40:41]
	s_waitcnt lgkmcnt(6)
; __device__ void scan_block(const Params& P, int sb, unsigned char* lds) {
;     ...
;       for (int s = 0; s < SC_CH; ++s) {
;         f32x4 w4n, k4n, b4n, kh4n, r4n; float vn;
;         if (s + 1 < SC_CH) {
;           const float* qn = q + (s + 1) * SC_STEP;
;           w4n = *(const f32x4*)(qn); k4n = *(const f32x4*)(qn + 64); b4n = *(const f32x4*)(qn + 128); kh4n = *(const f32x4*)(qn + 192); r4n = *(const f32x4*)(qn + 256);
;           vn = qv[(s + 1) * SC_STEP];
;         }
;         __builtin_amdgcn_sched_barrier(0);
;         if (s > 0) {
;           const float y = dpp_allreduce16(ypart);
;           yk = (ks == ((s - 1) & 15)) ? y : yk;
;           if (((s - 1) & 15) == 15) yo[(size_t)(s - 16) * 1024] = yk;
;         }
;         const f32x2 pp = (f32x2){S[0], S[1]} * (f32x2){k4[0], k4[1]} + (f32x2){S[2], S[3]} * (f32x2){k4[2], k4[3]};
;         const f32x4 A = S * w4 + v * kh4;
;         const float ar = dpp_allreduce16(pp.x + pp.y);
;         S = A + ar * b4;
;         const f32x2 yy = (f32x2){S[0], S[1]} * (f32x2){r4[0], r4[1]} + (f32x2){S[2], S[3]} * (f32x2){r4[2], r4[3]};
;         ypart = yy.x + yy.y;
;         if (s + 1 < SC_CH) { w4 = w4n; k4 = k4n; b4 = b4n; kh4 = kh4n; r4 = r4n; v = vn; }
;       }
	v_pk_mul_f32 v[52:53], v[6:7], v[62:63]
	v_pk_mul_f32 v[56:57], v[6:7], v[66:67]
	v_pk_fma_f32 v[52:53], v[4:5], v[60:61], v[52:53]
	v_pk_mul_f32 v[54:55], v[4:5], v[64:65]
	v_add_f32_e32 v52, v52, v53
	ds_read_b128 v[60:63], v9 offset:28480
	ds_read_b128 v[64:67], v9 offset:28224
	v_add_f32_dpp v52, v52, v52 quad_perm:[1,0,3,2] row_mask:0xf bank_mask:0xf bound_ctrl:1
	v_pk_fma_f32 v[56:57], v[30:31], v[32:33], v[56:57] op_sel_hi:[1,0,1]
	v_pk_fma_f32 v[54:55], v[28:29], v[32:33], v[54:55] op_sel_hi:[1,0,1]
	v_add_f32_dpp v52, v52, v52 quad_perm:[2,3,0,1] row_mask:0xf bank_mask:0xf bound_ctrl:1
	ds_read_b128 v[28:31], v9 offset:28992
	ds_read_b32 v32, v10 offset:29504
	v_add_f32_dpp v52, v52, v52 row_half_mirror row_mask:0xf bank_mask:0xf bound_ctrl:1
	v_pk_mul_f32 v[26:27], v[6:7], v[38:39]
	v_add_f32_dpp v34, v25, v25 row_ror:8 row_mask:0xf bank_mask:0xc
	v_add_f32_dpp v52, v52, v52 row_mirror row_mask:0xf bank_mask:0xf bound_ctrl:1
	v_pk_fma_f32 v[6:7], v[50:51], v[52:53], v[56:57] op_sel_hi:[1,0,1]
	v_pk_fma_f32 v[26:27], v[4:5], v[36:37], v[26:27]
	v_pk_fma_f32 v[4:5], v[48:49], v[52:53], v[54:55] op_sel_hi:[1,0,1]
	ds_read_b128 v[36:39], v9 offset:27904
	ds_read_b128 v[48:51], v9 offset:28736
	v_add_f32_e32 v25, v26, v27
	v_add_f32_dpp v35, v34, v34 row_half_mirror row_mask:0xf bank_mask:0x5
	s_waitcnt lgkmcnt(6)
	v_pk_mul_f32 v[52:53], v[6:7], v[14:15]
	v_pk_mul_f32 v[56:57], v[6:7], v[18:19]
	v_pk_fma_f32 v[52:53], v[4:5], v[12:13], v[52:53]
	v_pk_mul_f32 v[54:55], v[4:5], v[16:17]
	v_add_f32_e32 v52, v52, v53
	ds_read_b128 v[12:15], v9 offset:29824
	ds_read_b128 v[16:19], v9 offset:29568
	v_add_f32_dpp v52, v52, v52 quad_perm:[1,0,3,2] row_mask:0xf bank_mask:0xf bound_ctrl:1
	v_pk_fma_f32 v[56:57], v[22:23], v[24:25], v[56:57] op_sel_hi:[1,0,1]
	v_pk_fma_f32 v[54:55], v[20:21], v[24:25], v[54:55] op_sel_hi:[1,0,1]
	v_add_f32_dpp v52, v52, v52 quad_perm:[2,3,0,1] row_mask:0xf bank_mask:0xf bound_ctrl:1
	ds_read_b128 v[20:23], v9 offset:30336
	ds_read_b32 v24, v10 offset:30848
	v_add_f32_dpp v52, v52, v52 row_half_mirror row_mask:0xf bank_mask:0xf bound_ctrl:1
	v_pk_mul_f32 v[26:27], v[6:7], v[42:43]
	v_add_f32_dpp v34, v25, v25 row_ror:8 row_mask:0xf bank_mask:0x3
	v_add_f32_dpp v52, v52, v52 row_mirror row_mask:0xf bank_mask:0xf bound_ctrl:1
	v_pk_fma_f32 v[6:7], v[46:47], v[52:53], v[56:57] op_sel_hi:[1,0,1]
	v_pk_fma_f32 v[26:27], v[4:5], v[40:41], v[26:27]
	v_pk_fma_f32 v[4:5], v[44:45], v[52:53], v[54:55] op_sel_hi:[1,0,1]
	ds_read_b128 v[40:43], v9 offset:29248
	ds_read_b128 v[44:47], v9 offset:30080
	v_add_f32_e32 v25, v26, v27
	v_cndmask_b32_e64 v8, v11, v0, s[40:41]
	s_waitcnt lgkmcnt(6)
	v_pk_mul_f32 v[52:53], v[6:7], v[62:63]
	v_pk_mul_f32 v[56:57], v[6:7], v[66:67]
	v_pk_fma_f32 v[52:53], v[4:5], v[60:61], v[52:53]
	v_pk_mul_f32 v[54:55], v[4:5], v[64:65]
	v_add_f32_e32 v52, v52, v53
	ds_read_b128 v[60:63], v9 offset:31168
	ds_read_b128 v[64:67], v9 offset:30912
	v_add_f32_dpp v52, v52, v52 quad_perm:[1,0,3,2] row_mask:0xf bank_mask:0xf bound_ctrl:1
	v_pk_fma_f32 v[56:57], v[30:31], v[32:33], v[56:57] op_sel_hi:[1,0,1]
	v_pk_fma_f32 v[54:55], v[28:29], v[32:33], v[54:55] op_sel_hi:[1,0,1]
	v_add_f32_dpp v52, v52, v52 quad_perm:[2,3,0,1] row_mask:0xf bank_mask:0xf bound_ctrl:1
	ds_read_b128 v[28:31], v9 offset:31680
	ds_read_b32 v32, v10 offset:32192
	v_add_f32_dpp v52, v52, v52 row_half_mirror row_mask:0xf bank_mask:0xf bound_ctrl:1
	v_pk_mul_f32 v[26:27], v[6:7], v[38:39]
	v_add_f32_dpp v34, v25, v25 row_ror:8 row_mask:0xf bank_mask:0xc
	v_add_f32_dpp v52, v52, v52 row_mirror row_mask:0xf bank_mask:0xf bound_ctrl:1
	v_pk_fma_f32 v[6:7], v[50:51], v[52:53], v[56:57] op_sel_hi:[1,0,1]
	v_pk_fma_f32 v[26:27], v[4:5], v[36:37], v[26:27]
	v_pk_fma_f32 v[4:5], v[48:49], v[52:53], v[54:55] op_sel_hi:[1,0,1]
	ds_read_b128 v[36:39], v9 offset:30592
	ds_read_b128 v[48:51], v9 offset:31424
	v_add_f32_e32 v25, v26, v27
	v_add_f32_dpp v35, v34, v34 row_half_mirror row_mask:0xf bank_mask:0xa
	s_waitcnt lgkmcnt(6)
	v_pk_mul_f32 v[52:53], v[6:7], v[14:15]
	v_pk_mul_f32 v[56:57], v[6:7], v[18:19]
	v_pk_fma_f32 v[52:53], v[4:5], v[12:13], v[52:53]
	v_pk_mul_f32 v[54:55], v[4:5], v[16:17]
	v_add_f32_e32 v52, v52, v53
	ds_read_b128 v[12:15], v9 offset:32512
	ds_read_b128 v[16:19], v9 offset:32256
	v_add_f32_dpp v52, v52, v52 quad_perm:[1,0,3,2] row_mask:0xf bank_mask:0xf bound_ctrl:1
	v_pk_fma_f32 v[56:57], v[22:23], v[24:25], v[56:57] op_sel_hi:[1,0,1]
	v_pk_fma_f32 v[54:55], v[20:21], v[24:25], v[54:55] op_sel_hi:[1,0,1]
	v_add_f32_dpp v52, v52, v52 quad_perm:[2,3,0,1] row_mask:0xf bank_mask:0xf bound_ctrl:1
	ds_read_b128 v[20:23], v9 offset:33024
	ds_read_b32 v24, v10 offset:33536
	v_add_f32_dpp v52, v52, v52 row_half_mirror row_mask:0xf bank_mask:0xf bound_ctrl:1
	v_pk_mul_f32 v[26:27], v[6:7], v[42:43]
	v_add_f32_dpp v34, v25, v25 row_ror:8 row_mask:0xf bank_mask:0x3
	v_add_f32_dpp v52, v52, v52 row_mirror row_mask:0xf bank_mask:0xf bound_ctrl:1
	v_pk_fma_f32 v[6:7], v[46:47], v[52:53], v[56:57] op_sel_hi:[1,0,1]
	v_pk_fma_f32 v[26:27], v[4:5], v[40:41], v[26:27]
	v_pk_fma_f32 v[4:5], v[44:45], v[52:53], v[54:55] op_sel_hi:[1,0,1]
	ds_read_b128 v[40:43], v9 offset:31936
	ds_read_b128 v[44:47], v9 offset:32768
	v_add_f32_e32 v25, v26, v27
	v_add_f32_dpp v254, v8, v255 quad_perm:[2,3,0,1] row_mask:0xf bank_mask:0xf bound_ctrl:1
	s_waitcnt lgkmcnt(6)
; __device__ void scan_block(const Params& P, int sb, unsigned char* lds) {
;     ...
;       for (int s = 0; s < SC_CH; ++s) {
;         f32x4 w4n, k4n, b4n, kh4n, r4n; float vn;
;         if (s + 1 < SC_CH) {
;           const float* qn = q + (s + 1) * SC_STEP;
;           w4n = *(const f32x4*)(qn); k4n = *(const f32x4*)(qn + 64); b4n = *(const f32x4*)(qn + 128); kh4n = *(const f32x4*)(qn + 192); r4n = *(const f32x4*)(qn + 256);
;           vn = qv[(s + 1) * SC_STEP];
;         }
;         __builtin_amdgcn_sched_barrier(0);
;         if (s > 0) {
;           const float y = dpp_allreduce16(ypart);
;           yk = (ks == ((s - 1) & 15)) ? y : yk;
;           if (((s - 1) & 15) == 15) yo[(size_t)(s - 16) * 1024] = yk;
;         }
;         const f32x2 pp = (f32x2){S[0], S[1]} * (f32x2){k4[0], k4[1]} + (f32x2){S[2], S[3]} * (f32x2){k4[2], k4[3]};
;         const f32x4 A = S * w4 + v * kh4;
;         const float ar = dpp_allreduce16(pp.x + pp.y);
;         S = A + ar * b4;
;         const f32x2 yy = (f32x2){S[0], S[1]} * (f32x2){r4[0], r4[1]} + (f32x2){S[2], S[3]} * (f32x2){r4[2], r4[3]};
;         ypart = yy.x + yy.y;
;         if (s + 1 < SC_CH) { w4 = w4n; k4 = k4n; b4 = b4n; kh4 = kh4n; r4 = r4n; v = vn; }
;       }
	v_pk_mul_f32 v[52:53], v[6:7], v[62:63]
	v_pk_mul_f32 v[56:57], v[6:7], v[66:67]
	v_pk_fma_f32 v[52:53], v[4:5], v[60:61], v[52:53]
	v_pk_mul_f32 v[54:55], v[4:5], v[64:65]
	v_add_f32_e32 v52, v52, v53
	ds_read_b128 v[60:63], v9 offset:33856
	ds_read_b128 v[64:67], v9 offset:33600
	v_add_f32_dpp v52, v52, v52 quad_perm:[1,0,3,2] row_mask:0xf bank_mask:0xf bound_ctrl:1
	v_pk_fma_f32 v[56:57], v[30:31], v[32:33], v[56:57] op_sel_hi:[1,0,1]
	v_pk_fma_f32 v[54:55], v[28:29], v[32:33], v[54:55] op_sel_hi:[1,0,1]
	v_add_f32_dpp v52, v52, v52 quad_perm:[2,3,0,1] row_mask:0xf bank_mask:0xf bound_ctrl:1
	ds_read_b128 v[28:31], v9 offset:34368
	ds_read_b32 v32, v10 offset:34880
	v_add_f32_dpp v52, v52, v52 row_half_mirror row_mask:0xf bank_mask:0xf bound_ctrl:1
	v_pk_mul_f32 v[26:27], v[6:7], v[38:39]
	v_add_f32_dpp v34, v25, v25 row_ror:8 row_mask:0xf bank_mask:0xc
	v_add_f32_dpp v52, v52, v52 row_mirror row_mask:0xf bank_mask:0xf bound_ctrl:1
	v_pk_fma_f32 v[6:7], v[50:51], v[52:53], v[56:57] op_sel_hi:[1,0,1]
	v_pk_fma_f32 v[26:27], v[4:5], v[36:37], v[26:27]
	v_pk_fma_f32 v[4:5], v[48:49], v[52:53], v[54:55] op_sel_hi:[1,0,1]
	ds_read_b128 v[36:39], v9 offset:33280
	ds_read_b128 v[48:51], v9 offset:34112
	v_add_f32_e32 v25, v26, v27
	v_add_f32_dpp v58, v34, v34 row_half_mirror row_mask:0xf bank_mask:0x5
	s_waitcnt lgkmcnt(6)
	v_pk_mul_f32 v[52:53], v[6:7], v[14:15]
	v_pk_mul_f32 v[56:57], v[6:7], v[18:19]
	v_pk_fma_f32 v[52:53], v[4:5], v[12:13], v[52:53]
	v_pk_mul_f32 v[54:55], v[4:5], v[16:17]
	v_add_f32_e32 v52, v52, v53
	ds_read_b128 v[12:15], v9 offset:35200
	ds_read_b128 v[16:19], v9 offset:34944
	v_add_f32_dpp v52, v52, v52 quad_perm:[1,0,3,2] row_mask:0xf bank_mask:0xf bound_ctrl:1
	v_pk_fma_f32 v[56:57], v[22:23], v[24:25], v[56:57] op_sel_hi:[1,0,1]
	v_pk_fma_f32 v[54:55], v[20:21], v[24:25], v[54:55] op_sel_hi:[1,0,1]
	v_add_f32_dpp v52, v52, v52 quad_perm:[2,3,0,1] row_mask:0xf bank_mask:0xf bound_ctrl:1
	ds_read_b128 v[20:23], v9 offset:35712
	ds_read_b32 v24, v10 offset:36224
	v_add_f32_dpp v52, v52, v52 row_half_mirror row_mask:0xf bank_mask:0xf bound_ctrl:1
	v_pk_mul_f32 v[26:27], v[6:7], v[42:43]
	v_add_f32_dpp v34, v25, v25 row_ror:8 row_mask:0xf bank_mask:0x3
	v_add_f32_dpp v52, v52, v52 row_mirror row_mask:0xf bank_mask:0xf bound_ctrl:1
	v_pk_fma_f32 v[6:7], v[46:47], v[52:53], v[56:57] op_sel_hi:[1,0,1]
	v_pk_fma_f32 v[26:27], v[4:5], v[40:41], v[26:27]
	v_pk_fma_f32 v[4:5], v[44:45], v[52:53], v[54:55] op_sel_hi:[1,0,1]
	ds_read_b128 v[40:43], v9 offset:34624
	ds_read_b128 v[44:47], v9 offset:35456
	v_add_f32_e32 v25, v26, v27
	v_cndmask_b32_e64 v255, v253, v254, s[42:43]
	s_waitcnt lgkmcnt(6)
	v_pk_mul_f32 v[52:53], v[6:7], v[62:63]
	v_pk_mul_f32 v[56:57], v[6:7], v[66:67]
	v_pk_fma_f32 v[52:53], v[4:5], v[60:61], v[52:53]
	v_pk_mul_f32 v[54:55], v[4:5], v[64:65]
	v_add_f32_e32 v52, v52, v53
	ds_read_b128 v[60:63], v9 offset:36544
	ds_read_b128 v[64:67], v9 offset:36288
	v_add_f32_dpp v52, v52, v52 quad_perm:[1,0,3,2] row_mask:0xf bank_mask:0xf bound_ctrl:1
	v_pk_fma_f32 v[56:57], v[30:31], v[32:33], v[56:57] op_sel_hi:[1,0,1]
	v_pk_fma_f32 v[54:55], v[28:29], v[32:33], v[54:55] op_sel_hi:[1,0,1]
	v_add_f32_dpp v52, v52, v52 quad_perm:[2,3,0,1] row_mask:0xf bank_mask:0xf bound_ctrl:1
	ds_read_b128 v[28:31], v9 offset:37056
	ds_read_b32 v32, v10 offset:37568
	v_add_f32_dpp v52, v52, v52 row_half_mirror row_mask:0xf bank_mask:0xf bound_ctrl:1
	v_pk_mul_f32 v[26:27], v[6:7], v[38:39]
	v_add_f32_dpp v34, v25, v25 row_ror:8 row_mask:0xf bank_mask:0xc
	v_add_f32_dpp v52, v52, v52 row_mirror row_mask:0xf bank_mask:0xf bound_ctrl:1
	v_pk_fma_f32 v[6:7], v[50:51], v[52:53], v[56:57] op_sel_hi:[1,0,1]
	v_pk_fma_f32 v[26:27], v[4:5], v[36:37], v[26:27]
	v_pk_fma_f32 v[4:5], v[48:49], v[52:53], v[54:55] op_sel_hi:[1,0,1]
	ds_read_b128 v[36:39], v9 offset:35968
	ds_read_b128 v[48:51], v9 offset:36800
	v_add_f32_e32 v25, v26, v27
	v_add_f32_dpp v58, v34, v34 row_half_mirror row_mask:0xf bank_mask:0xa
	s_waitcnt lgkmcnt(6)
	v_pk_mul_f32 v[52:53], v[6:7], v[14:15]
	v_pk_mul_f32 v[56:57], v[6:7], v[18:19]
	v_pk_fma_f32 v[52:53], v[4:5], v[12:13], v[52:53]
	v_pk_mul_f32 v[54:55], v[4:5], v[16:17]
	v_add_f32_e32 v52, v52, v53
	ds_read_b128 v[12:15], v9 offset:37888
	ds_read_b128 v[16:19], v9 offset:37632
	v_add_f32_dpp v52, v52, v52 quad_perm:[1,0,3,2] row_mask:0xf bank_mask:0xf bound_ctrl:1
	v_pk_fma_f32 v[56:57], v[22:23], v[24:25], v[56:57] op_sel_hi:[1,0,1]
	v_pk_fma_f32 v[54:55], v[20:21], v[24:25], v[54:55] op_sel_hi:[1,0,1]
	v_add_f32_dpp v52, v52, v52 quad_perm:[2,3,0,1] row_mask:0xf bank_mask:0xf bound_ctrl:1
	ds_read_b128 v[20:23], v9 offset:38400
	ds_read_b32 v24, v10 offset:38912
	v_add_f32_dpp v52, v52, v52 row_half_mirror row_mask:0xf bank_mask:0xf bound_ctrl:1
	v_pk_mul_f32 v[26:27], v[6:7], v[42:43]
	v_add_f32_dpp v34, v25, v25 row_ror:8 row_mask:0xf bank_mask:0x3
	v_add_f32_dpp v52, v52, v52 row_mirror row_mask:0xf bank_mask:0xf bound_ctrl:1
	v_pk_fma_f32 v[6:7], v[46:47], v[52:53], v[56:57] op_sel_hi:[1,0,1]
	v_pk_fma_f32 v[26:27], v[4:5], v[40:41], v[26:27]
	v_pk_fma_f32 v[4:5], v[44:45], v[52:53], v[54:55] op_sel_hi:[1,0,1]
	ds_read_b128 v[40:43], v9 offset:37312
	ds_read_b128 v[44:47], v9 offset:38144
	v_add_f32_e32 v25, v26, v27
	v_cndmask_b32_e64 v8, v254, v253, s[42:43]
	s_waitcnt lgkmcnt(6)
; __device__ void scan_block(const Params& P, int sb, unsigned char* lds) {
;     ...
;       for (int s = 0; s < SC_CH; ++s) {
;         f32x4 w4n, k4n, b4n, kh4n, r4n; float vn;
;         if (s + 1 < SC_CH) {
;           const float* qn = q + (s + 1) * SC_STEP;
;           w4n = *(const f32x4*)(qn); k4n = *(const f32x4*)(qn + 64); b4n = *(const f32x4*)(qn + 128); kh4n = *(const f32x4*)(qn + 192); r4n = *(const f32x4*)(qn + 256);
;           vn = qv[(s + 1) * SC_STEP];
;         }
;         __builtin_amdgcn_sched_barrier(0);
;         if (s > 0) {
;           const float y = dpp_allreduce16(ypart);
;           yk = (ks == ((s - 1) & 15)) ? y : yk;
;           if (((s - 1) & 15) == 15) yo[(size_t)(s - 16) * 1024] = yk;
;         }
;         const f32x2 pp = (f32x2){S[0], S[1]} * (f32x2){k4[0], k4[1]} + (f32x2){S[2], S[3]} * (f32x2){k4[2], k4[3]};
;         const f32x4 A = S * w4 + v * kh4;
;         const float ar = dpp_allreduce16(pp.x + pp.y);
;         S = A + ar * b4;
;         const f32x2 yy = (f32x2){S[0], S[1]} * (f32x2){r4[0], r4[1]} + (f32x2){S[2], S[3]} * (f32x2){r4[2], r4[3]};
;         ypart = yy.x + yy.y;
;         if (s + 1 < SC_CH) { w4 = w4n; k4 = k4n; b4 = b4n; kh4 = kh4n; r4 = r4n; v = vn; }
;       }
;       { const float y = dpp_allreduce16(ypart); yk = (ks == 15) ? y : yk; yo[(size_t)16 * 1024] = yk; }
	v_pk_mul_f32 v[52:53], v[6:7], v[62:63]
	v_pk_mul_f32 v[56:57], v[6:7], v[66:67]
	v_pk_fma_f32 v[52:53], v[4:5], v[60:61], v[52:53]
	v_pk_mul_f32 v[54:55], v[4:5], v[64:65]
	v_add_f32_e32 v52, v52, v53
	ds_read_b128 v[60:63], v9 offset:39232
	ds_read_b128 v[64:67], v9 offset:38976
	v_add_f32_dpp v52, v52, v52 quad_perm:[1,0,3,2] row_mask:0xf bank_mask:0xf bound_ctrl:1
	v_pk_fma_f32 v[56:57], v[30:31], v[32:33], v[56:57] op_sel_hi:[1,0,1]
	v_pk_fma_f32 v[54:55], v[28:29], v[32:33], v[54:55] op_sel_hi:[1,0,1]
	v_add_f32_dpp v52, v52, v52 quad_perm:[2,3,0,1] row_mask:0xf bank_mask:0xf bound_ctrl:1
	ds_read_b128 v[28:31], v9 offset:39744
	ds_read_b32 v32, v10 offset:40256
	v_add_f32_dpp v52, v52, v52 row_half_mirror row_mask:0xf bank_mask:0xf bound_ctrl:1
	v_pk_mul_f32 v[26:27], v[6:7], v[38:39]
	v_add_f32_dpp v34, v25, v25 row_ror:8 row_mask:0xf bank_mask:0xc
	v_add_f32_dpp v52, v52, v52 row_mirror row_mask:0xf bank_mask:0xf bound_ctrl:1
	v_pk_fma_f32 v[6:7], v[50:51], v[52:53], v[56:57] op_sel_hi:[1,0,1]
	v_pk_fma_f32 v[26:27], v[4:5], v[36:37], v[26:27]
	v_pk_fma_f32 v[4:5], v[48:49], v[52:53], v[54:55] op_sel_hi:[1,0,1]
	ds_read_b128 v[36:39], v9 offset:38656
	ds_read_b128 v[48:51], v9 offset:39488
	v_add_f32_e32 v25, v26, v27
	v_add_f32_dpp v0, v34, v34 row_half_mirror row_mask:0xf bank_mask:0x5
	s_waitcnt lgkmcnt(6)
	v_pk_mul_f32 v[52:53], v[6:7], v[14:15]
	v_pk_mul_f32 v[56:57], v[6:7], v[18:19]
	v_pk_fma_f32 v[52:53], v[4:5], v[12:13], v[52:53]
	v_pk_mul_f32 v[54:55], v[4:5], v[16:17]
	v_add_f32_e32 v52, v52, v53
	ds_read_b128 v[12:15], v9 offset:40576
	ds_read_b128 v[16:19], v9 offset:40320
	v_add_f32_dpp v52, v52, v52 quad_perm:[1,0,3,2] row_mask:0xf bank_mask:0xf bound_ctrl:1
	v_pk_fma_f32 v[56:57], v[22:23], v[24:25], v[56:57] op_sel_hi:[1,0,1]
	v_pk_fma_f32 v[54:55], v[20:21], v[24:25], v[54:55] op_sel_hi:[1,0,1]
	v_add_f32_dpp v52, v52, v52 quad_perm:[2,3,0,1] row_mask:0xf bank_mask:0xf bound_ctrl:1
	ds_read_b128 v[20:23], v9 offset:41088
	ds_read_b32 v24, v10 offset:41600
	v_add_f32_dpp v52, v52, v52 row_half_mirror row_mask:0xf bank_mask:0xf bound_ctrl:1
	v_pk_mul_f32 v[26:27], v[6:7], v[42:43]
	v_add_f32_dpp v34, v25, v25 row_ror:8 row_mask:0xf bank_mask:0x3
	v_add_f32_dpp v52, v52, v52 row_mirror row_mask:0xf bank_mask:0xf bound_ctrl:1
	v_pk_fma_f32 v[6:7], v[46:47], v[52:53], v[56:57] op_sel_hi:[1,0,1]
	v_pk_fma_f32 v[26:27], v[4:5], v[40:41], v[26:27]
	v_pk_fma_f32 v[4:5], v[44:45], v[52:53], v[54:55] op_sel_hi:[1,0,1]
	ds_read_b128 v[40:43], v9 offset:40000
	ds_read_b128 v[44:47], v9 offset:40832
	v_add_f32_e32 v25, v26, v27
	v_add_f32_dpp v33, v8, v255 quad_perm:[1,0,3,2] row_mask:0xf bank_mask:0xf bound_ctrl:1
	s_waitcnt lgkmcnt(6)
	v_pk_mul_f32 v[52:53], v[6:7], v[62:63]
	v_pk_mul_f32 v[56:57], v[6:7], v[66:67]
	v_pk_fma_f32 v[52:53], v[4:5], v[60:61], v[52:53]
	v_pk_mul_f32 v[54:55], v[4:5], v[64:65]
	v_add_f32_e32 v52, v52, v53
	ds_read_b128 v[60:63], v9 offset:41920
	ds_read_b128 v[64:67], v9 offset:41664
	v_add_f32_dpp v52, v52, v52 quad_perm:[1,0,3,2] row_mask:0xf bank_mask:0xf bound_ctrl:1
	v_pk_fma_f32 v[56:57], v[30:31], v[32:33], v[56:57] op_sel_hi:[1,0,1]
	v_pk_fma_f32 v[54:55], v[28:29], v[32:33], v[54:55] op_sel_hi:[1,0,1]
	v_add_f32_dpp v52, v52, v52 quad_perm:[2,3,0,1] row_mask:0xf bank_mask:0xf bound_ctrl:1
	ds_read_b128 v[28:31], v9 offset:42432
	ds_read_b32 v32, v10 offset:42944
	v_add_f32_dpp v52, v52, v52 row_half_mirror row_mask:0xf bank_mask:0xf bound_ctrl:1
	v_pk_mul_f32 v[26:27], v[6:7], v[38:39]
	v_add_f32_dpp v34, v25, v25 row_ror:8 row_mask:0xf bank_mask:0xc
	v_add_f32_dpp v52, v52, v52 row_mirror row_mask:0xf bank_mask:0xf bound_ctrl:1
	v_pk_fma_f32 v[6:7], v[50:51], v[52:53], v[56:57] op_sel_hi:[1,0,1]
	v_pk_fma_f32 v[26:27], v[4:5], v[36:37], v[26:27]
	v_pk_fma_f32 v[4:5], v[48:49], v[52:53], v[54:55] op_sel_hi:[1,0,1]
	ds_read_b128 v[36:39], v9 offset:41344
	ds_read_b128 v[48:51], v9 offset:42176
	v_add_f32_e32 v25, v26, v27
	v_add_f32_dpp v0, v34, v34 row_half_mirror row_mask:0xf bank_mask:0xa
	s_waitcnt lgkmcnt(6)
	v_pk_mul_f32 v[52:53], v[6:7], v[14:15]
	v_pk_mul_f32 v[56:57], v[6:7], v[18:19]
	v_pk_fma_f32 v[52:53], v[4:5], v[12:13], v[52:53]
	v_pk_mul_f32 v[54:55], v[4:5], v[16:17]
	v_add_f32_e32 v52, v52, v53
	s_nop 1
	v_add_f32_dpp v52, v52, v52 quad_perm:[1,0,3,2] row_mask:0xf bank_mask:0xf bound_ctrl:1
	v_pk_fma_f32 v[56:57], v[22:23], v[24:25], v[56:57] op_sel_hi:[1,0,1]
	v_pk_fma_f32 v[54:55], v[20:21], v[24:25], v[54:55] op_sel_hi:[1,0,1]
	v_add_f32_dpp v52, v52, v52 quad_perm:[2,3,0,1] row_mask:0xf bank_mask:0xf bound_ctrl:1
	s_nop 1
	v_add_f32_dpp v52, v52, v52 row_half_mirror row_mask:0xf bank_mask:0xf bound_ctrl:1
	v_pk_mul_f32 v[26:27], v[6:7], v[42:43]
	v_add_f32_dpp v34, v25, v25 row_ror:8 row_mask:0xf bank_mask:0x3
	v_add_f32_dpp v52, v52, v52 row_mirror row_mask:0xf bank_mask:0xf bound_ctrl:1
	v_pk_fma_f32 v[6:7], v[46:47], v[52:53], v[56:57] op_sel_hi:[1,0,1]
	v_pk_fma_f32 v[26:27], v[4:5], v[40:41], v[26:27]
	v_pk_fma_f32 v[4:5], v[44:45], v[52:53], v[54:55] op_sel_hi:[1,0,1]
	ds_read_b128 v[40:43], v9 offset:42688
	v_add_f32_e32 v25, v26, v27
	global_store_dword v2, v33, s[4:5]
	s_waitcnt lgkmcnt(1)
	v_pk_mul_f32 v[52:53], v[6:7], v[62:63]
	v_pk_mul_f32 v[56:57], v[6:7], v[66:67]
	v_pk_fma_f32 v[52:53], v[4:5], v[60:61], v[52:53]
	v_pk_mul_f32 v[54:55], v[4:5], v[64:65]
	v_add_f32_e32 v52, v52, v53
	s_nop 1
	v_add_f32_dpp v52, v52, v52 quad_perm:[1,0,3,2] row_mask:0xf bank_mask:0xf bound_ctrl:1
	v_pk_fma_f32 v[56:57], v[30:31], v[32:33], v[56:57] op_sel_hi:[1,0,1]
	v_pk_fma_f32 v[54:55], v[28:29], v[32:33], v[54:55] op_sel_hi:[1,0,1]
	v_add_f32_dpp v52, v52, v52 quad_perm:[2,3,0,1] row_mask:0xf bank_mask:0xf bound_ctrl:1
	s_nop 1
	v_add_f32_dpp v52, v52, v52 row_half_mirror row_mask:0xf bank_mask:0xf bound_ctrl:1
	v_pk_mul_f32 v[26:27], v[6:7], v[38:39]
	v_add_f32_dpp v34, v25, v25 row_ror:8 row_mask:0xf bank_mask:0xc
	v_add_f32_dpp v52, v52, v52 row_mirror row_mask:0xf bank_mask:0xf bound_ctrl:1
	v_pk_fma_f32 v[6:7], v[50:51], v[52:53], v[56:57] op_sel_hi:[1,0,1]
	v_pk_fma_f32 v[26:27], v[4:5], v[36:37], v[26:27]
	v_pk_fma_f32 v[4:5], v[48:49], v[52:53], v[54:55] op_sel_hi:[1,0,1]
	v_add_f32_e32 v25, v26, v27
	v_add_f32_dpp v11, v34, v34 row_half_mirror row_mask:0xf bank_mask:0x5
	s_waitcnt lgkmcnt(0)
	s_barrier
; __device__ void scan_block(const Params& P, int sb, unsigned char* lds) {
;     ...
;       { const float y = dpp_allreduce16(ypart); yk = (ks == 15) ? y : yk; yo[(size_t)16 * 1024] = yk; }
;       __syncthreads();
;     }
	v_xor_b32_e32 v9, 0xa800, v9
	v_xor_b32_e32 v10, 0xa800, v10
	ds_read_b128 v[12:15], v9 offset:256
	ds_read_b128 v[16:19], v9 offset:0
	v_add_f32_dpp v34, v25, v25 row_ror:8 row_mask:0xf bank_mask:0x3
	v_pk_mul_f32 v[26:27], v[6:7], v[42:43]
	ds_read_b128 v[20:23], v9 offset:768
	v_cndmask_b32_e64 v255, v35, v58, s[40:41]
	v_cndmask_b32_e64 v8, v58, v35, s[40:41]
	v_pk_fma_f32 v[26:27], v[4:5], v[40:41], v[26:27]
	ds_read_b32 v24, v10 offset:1280
	v_add_f32_e32 v25, v26, v27
	ds_read_b128 v[44:47], v9 offset:512
	v_add_f32_dpp v253, v8, v255 quad_perm:[2,3,0,1] row_mask:0xf bank_mask:0xf bound_ctrl:1
	v_add_f32_dpp v34, v25, v25 row_ror:8 row_mask:0xf bank_mask:0xc
	ds_read_b128 v[36:39], v9 offset:1024
	ds_read_b128 v[60:63], v9 offset:1600
	v_add_f32_dpp v11, v34, v34 row_half_mirror row_mask:0xf bank_mask:0xa
	ds_read_b128 v[64:67], v9 offset:1344
	ds_read_b128 v[28:31], v9 offset:2112
	v_cndmask_b32_e64 v255, v0, v11, s[40:41]
	v_cndmask_b32_e64 v8, v11, v0, s[40:41]
	ds_read_b32 v32, v10 offset:2624
	ds_read_b128 v[48:51], v9 offset:1856
	v_add_f32_dpp v254, v8, v255 quad_perm:[2,3,0,1] row_mask:0xf bank_mask:0xf bound_ctrl:1
	v_cndmask_b32_e64 v255, v253, v254, s[42:43]
	v_cndmask_b32_e64 v8, v254, v253, s[42:43]
	s_add_i32 s3, s3, 1
	s_nop 0
	v_add_f32_dpp v33, v8, v255 quad_perm:[1,0,3,2] row_mask:0xf bank_mask:0xf bound_ctrl:1
	global_store_dword v3, v33, s[4:5]
	s_add_u32 s4, s4, 0x20000
	s_addc_u32 s5, s5, 0
	s_cmp_lg_u32 s3, 0x100
	s_cbranch_scc1 .Lscan_top
	s_waitcnt lgkmcnt(0)
	s_setprio 0
	v_readlane_b32 s60, v250, 1
	v_readlane_b32 s61, v250, 2
	s_mov_b64 s[62:63], s[90:91]
